# NSA window-branch full tiles: same lazy running-max scheme as the selected branch
# speedup vs baseline: 1.0334x; 1.0076x over previous
.Lwinf_go:
	v_min3_f32 v84, v184, v182, v170
	v_min_f32_e32 v84, v84, v188
	v_cmp_gt_f32_e32 vcc, 0xefa18f08, v84
	s_nop 1
	s_cbranch_vccnz .Lwinf_ex
	v_add_u32_e32 v134, s10, v208
	v_add_u32_e32 v250, v134, v149
	v_add_u32_e32 v251, v134, v155
	v_add_u32_e32 v254, v147, v149
	v_add_u32_e32 v255, v147, v155
	v_add_u32_e32 v194, v134, v210
	v_add_u32_e32 v195, v134, v211
	v_add_u32_e32 v196, v134, v212
	v_add_u32_e32 v197, v134, v213
	ds_read_b128 v[52:55], v250
	ds_read_b128 v[56:59], v250 offset:2048
	ds_read_b128 v[60:63], v251
	ds_read_b128 v[64:67], v251 offset:2048
	ds_read_b128 v[104:107], v254 offset:32768
	ds_read_b128 v[108:111], v255 offset:32768
	ds_read_b128 v[112:115], v254 offset:40960
	ds_read_b128 v[116:119], v255 offset:40960
	ds_read_b64 v[68:69], v194 offset:8192
	ds_read_b64 v[70:71], v195 offset:8192
	ds_read_b64 v[72:73], v194 offset:10240
	ds_read_b64 v[74:75], v195 offset:10240
	ds_read_b64 v[76:77], v194 offset:12288
	ds_read_b64 v[78:79], v195 offset:12288
	ds_read_b64 v[80:81], v194 offset:14336
	ds_read_b64 v[82:83], v195 offset:14336
	v_sub_f32_e32 v224, 0, v184
	v_sub_f32_e32 v225, 0, v184
	v_sub_f32_e32 v226, 0, v184
	v_sub_f32_e32 v227, 0, v184
	v_sub_f32_e32 v228, 0, v182
	v_sub_f32_e32 v229, 0, v182
	v_sub_f32_e32 v230, 0, v182
	v_sub_f32_e32 v231, 0, v182
	v_sub_f32_e32 v232, 0, v170
	v_sub_f32_e32 v233, 0, v170
	v_sub_f32_e32 v234, 0, v170
	v_sub_f32_e32 v235, 0, v170
	v_sub_f32_e32 v246, 0, v188
	v_sub_f32_e32 v247, 0, v188
	v_sub_f32_e32 v248, 0, v188
	v_sub_f32_e32 v249, 0, v188
	s_waitcnt lgkmcnt(8)
	v_mfma_f32_16x16x32_bf16 v[120:123], v[52:55], v[104:107], v[224:227]
	v_mfma_f32_16x16x32_bf16 v[124:127], v[56:59], v[104:107], v[224:227]
	v_mfma_f32_16x16x32_bf16 v[128:131], v[52:55], v[112:115], v[228:231]
	v_mfma_f32_16x16x32_bf16 v[172:175], v[56:59], v[112:115], v[228:231]
	v_mfma_f32_16x16x32_bf16 v[120:123], v[60:63], v[108:111], v[120:123]
	v_mfma_f32_16x16x32_bf16 v[124:127], v[64:67], v[108:111], v[124:127]
	v_mfma_f32_16x16x32_bf16 v[128:131], v[60:63], v[116:119], v[128:131]
	v_mfma_f32_16x16x32_bf16 v[172:175], v[64:67], v[116:119], v[172:175]
	ds_read_b128 v[104:107], v254 offset:49152
	ds_read_b128 v[108:111], v255 offset:49152
	ds_read_b128 v[112:115], v254 offset:57344
	ds_read_b128 v[116:119], v255 offset:57344
	v_max3_f32 v84, v120, s75, v121
	v_max3_f32 v84, v84, v122, v123
	v_max3_f32 v84, v84, v124, v125
	v_max3_f32 v84, v84, v126, v127
	v_max3_f32 v85, v128, s75, v129
	v_max3_f32 v85, v85, v130, v131
	v_max3_f32 v85, v85, v172, v173
	v_max3_f32 v85, v85, v174, v175
	v_max_f32_e32 v84, v84, v85
	v_cmp_lt_f32_e32 vcc, 0x41000000, v84
	s_nop 1
	s_cbranch_vccnz .Lwinf_fb0
	s_waitcnt lgkmcnt(0)
	v_mfma_f32_16x16x32_bf16 v[176:179], v[52:55], v[104:107], v[232:235]
	v_exp_f32_e32 v120, v120
	v_exp_f32_e32 v121, v121
	v_exp_f32_e32 v122, v122
	v_exp_f32_e32 v123, v123
	v_exp_f32_e32 v124, v124
	v_mfma_f32_16x16x32_bf16 v[190:193], v[56:59], v[104:107], v[232:235]
	v_exp_f32_e32 v125, v125
	v_exp_f32_e32 v126, v126
	v_exp_f32_e32 v127, v127
	v_exp_f32_e32 v128, v128
	v_exp_f32_e32 v129, v129
	v_mfma_f32_16x16x32_bf16 v[238:241], v[52:55], v[112:115], v[246:249]
	v_exp_f32_e32 v130, v130
	v_exp_f32_e32 v131, v131
	v_exp_f32_e32 v172, v172
	v_exp_f32_e32 v173, v173
	v_exp_f32_e32 v174, v174
	v_mfma_f32_16x16x32_bf16 v[242:245], v[56:59], v[112:115], v[246:249]
	v_exp_f32_e32 v175, v175
	v_add_f32_e32 v84, v120, v121
	v_add_f32_e32 v86, v122, v123
	v_add_f32_e32 v84, v84, v86
	v_add_f32_e32 v86, v124, v125
	v_mfma_f32_16x16x32_bf16 v[176:179], v[60:63], v[108:111], v[176:179]
	v_add_f32_e32 v84, v84, v86
	v_add_f32_e32 v86, v126, v127
	v_add_f32_e32 v84, v84, v86
	v_add_f32_e32 v133, v133, v84
	v_add_f32_e32 v85, v128, v129
	v_mfma_f32_16x16x32_bf16 v[190:193], v[64:67], v[108:111], v[190:193]
	v_add_f32_e32 v87, v130, v131
	v_add_f32_e32 v85, v85, v87
	v_add_f32_e32 v87, v172, v173
	v_add_f32_e32 v85, v85, v87
	v_add_f32_e32 v87, v174, v175
	v_mfma_f32_16x16x32_bf16 v[238:241], v[60:63], v[116:119], v[238:241]
	v_add_f32_e32 v85, v85, v87
	v_add_f32_e32 v132, v132, v85
	v_cvt_pk_bf16_f32 v120, v120, v121
	v_cvt_pk_bf16_f32 v121, v122, v123
	v_cvt_pk_bf16_f32 v122, v124, v125
	v_mfma_f32_16x16x32_bf16 v[242:245], v[64:67], v[116:119], v[242:245]
	ds_read_b128 v[52:55], v250 offset:4096
	ds_read_b128 v[56:59], v250 offset:6144
	ds_read_b128 v[60:63], v251 offset:4096
	ds_read_b128 v[64:67], v251 offset:6144
	ds_read_b128 v[104:107], v254 offset:32768
	ds_read_b128 v[108:111], v255 offset:32768
	ds_read_b128 v[112:115], v254 offset:40960
	ds_read_b128 v[116:119], v255 offset:40960
	v_cvt_pk_bf16_f32 v123, v126, v127
	v_cvt_pk_bf16_f32 v128, v128, v129
	v_cvt_pk_bf16_f32 v129, v130, v131
	v_cvt_pk_bf16_f32 v130, v172, v173
	v_cvt_pk_bf16_f32 v131, v174, v175
	s_waitcnt lgkmcnt(12)
	v_mfma_f32_16x16x32_bf16 v[100:103], v[68:71], v[120:123], v[100:103]
	v_max3_f32 v84, v176, s75, v177
	v_max3_f32 v84, v84, v178, v179
	v_max3_f32 v84, v84, v190, v191
	v_max3_f32 v84, v84, v192, v193
	v_max3_f32 v85, v238, s75, v239
	v_max3_f32 v85, v85, v240, v241
	v_max3_f32 v85, v85, v242, v243
	v_max3_f32 v85, v85, v244, v245
	v_max_f32_e32 v84, v84, v85
	v_cmp_lt_f32_e32 vcc, 0x41000000, v84
	s_nop 1
	s_cbranch_vccnz .Lwinf_fb1
	v_mfma_f32_16x16x32_bf16 v[36:39], v[68:71], v[128:131], v[36:39]
	v_exp_f32_e32 v176, v176
	v_exp_f32_e32 v177, v177
	v_exp_f32_e32 v178, v178
	v_mfma_f32_16x16x32_bf16 v[96:99], v[72:75], v[120:123], v[96:99]
	v_exp_f32_e32 v179, v179
	v_exp_f32_e32 v190, v190
	v_exp_f32_e32 v191, v191
	v_mfma_f32_16x16x32_bf16 v[32:35], v[72:75], v[128:131], v[32:35]
	v_exp_f32_e32 v192, v192
	v_exp_f32_e32 v193, v193
	v_mfma_f32_16x16x32_bf16 v[92:95], v[76:79], v[120:123], v[92:95]
	v_exp_f32_e32 v238, v238
	v_exp_f32_e32 v239, v239
	v_exp_f32_e32 v240, v240
	v_mfma_f32_16x16x32_bf16 v[28:31], v[76:79], v[128:131], v[28:31]
	v_exp_f32_e32 v241, v241
	v_exp_f32_e32 v242, v242
	v_exp_f32_e32 v243, v243
	v_mfma_f32_16x16x32_bf16 v[88:91], v[80:83], v[120:123], v[88:91]
	v_exp_f32_e32 v244, v244
	v_exp_f32_e32 v245, v245
	v_mfma_f32_16x16x32_bf16 v[24:27], v[80:83], v[128:131], v[24:27]
	v_add_f32_e32 v84, v176, v177
	v_add_f32_e32 v86, v178, v179
	v_add_f32_e32 v84, v84, v86
	s_waitcnt lgkmcnt(0)
	v_mfma_f32_16x16x32_bf16 v[120:123], v[52:55], v[104:107], v[224:227]
	v_add_f32_e32 v86, v190, v191
	v_add_f32_e32 v84, v84, v86
	v_add_f32_e32 v86, v192, v193
	v_mfma_f32_16x16x32_bf16 v[124:127], v[56:59], v[104:107], v[224:227]
	v_add_f32_e32 v84, v84, v86
	v_add_f32_e32 v165, v165, v84
	v_mfma_f32_16x16x32_bf16 v[128:131], v[52:55], v[112:115], v[228:231]
	v_add_f32_e32 v85, v238, v239
	v_add_f32_e32 v87, v240, v241
	v_add_f32_e32 v85, v85, v87
	v_mfma_f32_16x16x32_bf16 v[172:175], v[56:59], v[112:115], v[228:231]
	v_add_f32_e32 v87, v242, v243
	v_add_f32_e32 v85, v85, v87
	v_add_f32_e32 v87, v244, v245
	v_mfma_f32_16x16x32_bf16 v[120:123], v[60:63], v[108:111], v[120:123]
	v_add_f32_e32 v85, v85, v87
	v_add_f32_e32 v164, v164, v85
	v_mfma_f32_16x16x32_bf16 v[124:127], v[64:67], v[108:111], v[124:127]
	v_cvt_pk_bf16_f32 v176, v176, v177
	v_cvt_pk_bf16_f32 v177, v178, v179
	v_cvt_pk_bf16_f32 v178, v190, v191
	v_mfma_f32_16x16x32_bf16 v[128:131], v[60:63], v[116:119], v[128:131]
	v_cvt_pk_bf16_f32 v179, v192, v193
	v_cvt_pk_bf16_f32 v238, v238, v239
	v_cvt_pk_bf16_f32 v239, v240, v241
	v_mfma_f32_16x16x32_bf16 v[172:175], v[64:67], v[116:119], v[172:175]
	ds_read_b128 v[104:107], v254 offset:49152
	ds_read_b128 v[108:111], v255 offset:49152
	ds_read_b128 v[112:115], v254 offset:57344
	ds_read_b128 v[116:119], v255 offset:57344
	v_cvt_pk_bf16_f32 v240, v242, v243
	v_cvt_pk_bf16_f32 v241, v244, v245
	v_mfma_f32_16x16x32_bf16 v[44:47], v[68:71], v[176:179], v[44:47]
	v_max3_f32 v84, v120, s75, v121
	v_max3_f32 v84, v84, v122, v123
	v_max3_f32 v84, v84, v124, v125
	v_max3_f32 v84, v84, v126, v127
	v_max3_f32 v85, v128, s75, v129
	v_max3_f32 v85, v85, v130, v131
	v_max3_f32 v85, v85, v172, v173
	v_max3_f32 v85, v85, v174, v175
	v_max_f32_e32 v84, v84, v85
	v_cmp_lt_f32_e32 vcc, 0x41000000, v84
	s_nop 1
	s_cbranch_vccnz .Lwinf_fb2
	v_mfma_f32_16x16x32_bf16 v[12:15], v[68:71], v[238:241], v[12:15]
	v_exp_f32_e32 v120, v120
	v_exp_f32_e32 v121, v121
	v_exp_f32_e32 v122, v122
	v_mfma_f32_16x16x32_bf16 v[40:43], v[72:75], v[176:179], v[40:43]
	v_exp_f32_e32 v123, v123
	v_exp_f32_e32 v124, v124
	v_exp_f32_e32 v125, v125
	v_mfma_f32_16x16x32_bf16 v[8:11], v[72:75], v[238:241], v[8:11]
	v_exp_f32_e32 v126, v126
	v_exp_f32_e32 v127, v127
	v_mfma_f32_16x16x32_bf16 v[20:23], v[76:79], v[176:179], v[20:23]
	v_exp_f32_e32 v128, v128
	v_exp_f32_e32 v129, v129
	v_exp_f32_e32 v130, v130
	v_mfma_f32_16x16x32_bf16 v[4:7], v[76:79], v[238:241], v[4:7]
	v_exp_f32_e32 v131, v131
	v_exp_f32_e32 v172, v172
	v_exp_f32_e32 v173, v173
	v_mfma_f32_16x16x32_bf16 v[16:19], v[80:83], v[176:179], v[16:19]
	v_exp_f32_e32 v174, v174
	v_exp_f32_e32 v175, v175
	v_mfma_f32_16x16x32_bf16 v[0:3], v[80:83], v[238:241], v[0:3]
	v_add_f32_e32 v84, v120, v121
	v_add_f32_e32 v86, v122, v123
	v_add_f32_e32 v84, v84, v86
	ds_read_b64 v[68:69], v196 offset:8192
	ds_read_b64 v[70:71], v197 offset:8192
	ds_read_b64 v[72:73], v196 offset:10240
	ds_read_b64 v[74:75], v197 offset:10240
	ds_read_b64 v[76:77], v196 offset:12288
	ds_read_b64 v[78:79], v197 offset:12288
	ds_read_b64 v[80:81], v196 offset:14336
	ds_read_b64 v[82:83], v197 offset:14336
	s_waitcnt lgkmcnt(8)
	v_mfma_f32_16x16x32_bf16 v[176:179], v[52:55], v[104:107], v[232:235]
	v_add_f32_e32 v86, v124, v125
	v_add_f32_e32 v84, v84, v86
	v_add_f32_e32 v86, v126, v127
	v_mfma_f32_16x16x32_bf16 v[190:193], v[56:59], v[104:107], v[232:235]
	v_add_f32_e32 v84, v84, v86
	v_add_f32_e32 v133, v133, v84
	v_mfma_f32_16x16x32_bf16 v[238:241], v[52:55], v[112:115], v[246:249]
	v_add_f32_e32 v85, v128, v129
	v_add_f32_e32 v87, v130, v131
	v_add_f32_e32 v85, v85, v87
	v_mfma_f32_16x16x32_bf16 v[242:245], v[56:59], v[112:115], v[246:249]
	v_add_f32_e32 v87, v172, v173
	v_add_f32_e32 v85, v85, v87
	v_add_f32_e32 v87, v174, v175
	v_mfma_f32_16x16x32_bf16 v[176:179], v[60:63], v[108:111], v[176:179]
	v_add_f32_e32 v85, v85, v87
	v_add_f32_e32 v132, v132, v85
	v_mfma_f32_16x16x32_bf16 v[190:193], v[64:67], v[108:111], v[190:193]
	v_cvt_pk_bf16_f32 v120, v120, v121
	v_cvt_pk_bf16_f32 v121, v122, v123
	v_cvt_pk_bf16_f32 v122, v124, v125
	v_mfma_f32_16x16x32_bf16 v[238:241], v[60:63], v[116:119], v[238:241]
	v_cvt_pk_bf16_f32 v123, v126, v127
	v_cvt_pk_bf16_f32 v128, v128, v129
	v_cvt_pk_bf16_f32 v129, v130, v131
	v_mfma_f32_16x16x32_bf16 v[242:245], v[64:67], v[116:119], v[242:245]
	v_cvt_pk_bf16_f32 v130, v172, v173
	v_cvt_pk_bf16_f32 v131, v174, v175
	s_waitcnt lgkmcnt(0)
	v_mfma_f32_16x16x32_bf16 v[100:103], v[68:71], v[120:123], v[100:103]
	v_max3_f32 v84, v176, s75, v177
	v_max3_f32 v84, v84, v178, v179
	v_max3_f32 v84, v84, v190, v191
	v_max3_f32 v84, v84, v192, v193
	v_max3_f32 v85, v238, s75, v239
	v_max3_f32 v85, v85, v240, v241
	v_max3_f32 v85, v85, v242, v243
	v_max3_f32 v85, v85, v244, v245
	v_max_f32_e32 v84, v84, v85
	v_cmp_lt_f32_e32 vcc, 0x41000000, v84
	s_nop 1
	s_cbranch_vccnz .Lwinf_fb3
	v_mfma_f32_16x16x32_bf16 v[36:39], v[68:71], v[128:131], v[36:39]
	v_exp_f32_e32 v176, v176
	v_exp_f32_e32 v177, v177
	v_exp_f32_e32 v178, v178
	v_exp_f32_e32 v179, v179
	v_exp_f32_e32 v190, v190
	v_exp_f32_e32 v191, v191
	v_mfma_f32_16x16x32_bf16 v[96:99], v[72:75], v[120:123], v[96:99]
	v_exp_f32_e32 v192, v192
	v_exp_f32_e32 v193, v193
	v_exp_f32_e32 v238, v238
	v_exp_f32_e32 v239, v239
	v_exp_f32_e32 v240, v240
	v_exp_f32_e32 v241, v241
	v_mfma_f32_16x16x32_bf16 v[32:35], v[72:75], v[128:131], v[32:35]
	v_exp_f32_e32 v242, v242
	v_exp_f32_e32 v243, v243
	v_exp_f32_e32 v244, v244
	v_exp_f32_e32 v245, v245
	v_add_f32_e32 v84, v176, v177
	v_add_f32_e32 v86, v178, v179
	v_mfma_f32_16x16x32_bf16 v[92:95], v[76:79], v[120:123], v[92:95]
	v_add_f32_e32 v84, v84, v86
	v_add_f32_e32 v86, v190, v191
	v_add_f32_e32 v84, v84, v86
	v_add_f32_e32 v86, v192, v193
	v_add_f32_e32 v84, v84, v86
	v_mfma_f32_16x16x32_bf16 v[28:31], v[76:79], v[128:131], v[28:31]
	v_add_f32_e32 v165, v165, v84
	v_add_f32_e32 v85, v238, v239
	v_add_f32_e32 v87, v240, v241
	v_add_f32_e32 v85, v85, v87
	v_add_f32_e32 v87, v242, v243
	v_add_f32_e32 v85, v85, v87
	v_mfma_f32_16x16x32_bf16 v[88:91], v[80:83], v[120:123], v[88:91]
	v_add_f32_e32 v87, v244, v245
	v_add_f32_e32 v85, v85, v87
	v_add_f32_e32 v164, v164, v85
	v_cvt_pk_bf16_f32 v176, v176, v177
	v_cvt_pk_bf16_f32 v177, v178, v179
	v_cvt_pk_bf16_f32 v178, v190, v191
	v_mfma_f32_16x16x32_bf16 v[24:27], v[80:83], v[128:131], v[24:27]
	v_cvt_pk_bf16_f32 v179, v192, v193
	v_cvt_pk_bf16_f32 v238, v238, v239
	v_cvt_pk_bf16_f32 v239, v240, v241
	v_cvt_pk_bf16_f32 v240, v242, v243
	v_cvt_pk_bf16_f32 v241, v244, v245
	v_mfma_f32_16x16x32_bf16 v[44:47], v[68:71], v[176:179], v[44:47]
	v_mfma_f32_16x16x32_bf16 v[12:15], v[68:71], v[238:241], v[12:15]
	v_mfma_f32_16x16x32_bf16 v[40:43], v[72:75], v[176:179], v[40:43]
	v_mfma_f32_16x16x32_bf16 v[8:11], v[72:75], v[238:241], v[8:11]
	v_mfma_f32_16x16x32_bf16 v[20:23], v[76:79], v[176:179], v[20:23]
	v_mfma_f32_16x16x32_bf16 v[4:7], v[76:79], v[238:241], v[4:7]
	v_mfma_f32_16x16x32_bf16 v[16:19], v[80:83], v[176:179], v[16:19]
	v_mfma_f32_16x16x32_bf16 v[0:3], v[80:83], v[238:241], v[0:3]
	s_waitcnt lgkmcnt(0)
	s_waitcnt vmcnt(0)
	s_barrier
	s_andn2_b64 vcc, exec, s[4:5]
	s_cmp_lg_u64 s[6:7], 0
	s_cselect_b32 s6, 1, 0
	s_xor_b32 s84, s84, s6
	s_cbranch_vccz .LBB0_69
	s_branch .Lwinf_latch
.Lwinf_fb0:
	v_add_f32_e32 v120, v120, v184
	v_add_f32_e32 v121, v121, v184
	v_add_f32_e32 v122, v122, v184
	v_add_f32_e32 v123, v123, v184
	v_add_f32_e32 v124, v124, v184
	v_add_f32_e32 v125, v125, v184
	v_add_f32_e32 v126, v126, v184
	v_add_f32_e32 v127, v127, v184
	v_add_f32_e32 v128, v128, v182
	v_add_f32_e32 v129, v129, v182
	v_add_f32_e32 v130, v130, v182
	v_add_f32_e32 v131, v131, v182
	v_add_f32_e32 v172, v172, v182
	v_add_f32_e32 v173, v173, v182
	v_add_f32_e32 v174, v174, v182
	v_add_f32_e32 v175, v175, v182
	s_branch .Lwinf_x0
.Lwinf_fb1:
	v_add_f32_e32 v176, v176, v170
	v_add_f32_e32 v177, v177, v170
	v_add_f32_e32 v178, v178, v170
	v_add_f32_e32 v179, v179, v170
	v_add_f32_e32 v190, v190, v170
	v_add_f32_e32 v191, v191, v170
	v_add_f32_e32 v192, v192, v170
	v_add_f32_e32 v193, v193, v170
	v_add_f32_e32 v238, v238, v188
	v_add_f32_e32 v239, v239, v188
	v_add_f32_e32 v240, v240, v188
	v_add_f32_e32 v241, v241, v188
	v_add_f32_e32 v242, v242, v188
	v_add_f32_e32 v243, v243, v188
	v_add_f32_e32 v244, v244, v188
	v_add_f32_e32 v245, v245, v188
	s_branch .Lwinf_x1

.Lwinf_x0:
	s_waitcnt lgkmcnt(0)
	v_mfma_f32_16x16x32_bf16 v[176:179], v[52:55], v[104:107], 0
	v_max3_f32 v84, v120, s75, v121
	v_max3_f32 v84, v84, v122, v123
	v_max3_f32 v84, v84, v124, v125
	v_max3_f32 v84, v84, v126, v127
	v_max3_f32 v85, v128, s75, v129
	v_max3_f32 v85, v85, v130, v131
	v_max3_f32 v85, v85, v172, v173
	v_max3_f32 v85, v85, v174, v175
	v_mov_b32_e32 v86, v84
	v_mov_b32_e32 v87, v85
	s_nop 1
	v_permlane16_swap_b32_e32 v84, v86
	v_permlane16_swap_b32_e32 v85, v87
	v_max_f32_e32 v84, v84, v86
	v_max_f32_e32 v85, v85, v87
	v_mov_b32_e32 v86, v84
	v_mov_b32_e32 v87, v85
	s_nop 1
	v_permlane32_swap_b32_e32 v84, v86
	v_permlane32_swap_b32_e32 v85, v87
	v_mfma_f32_16x16x32_bf16 v[190:193], v[56:59], v[104:107], 0
	v_max3_f32 v84, v184, v84, v86
	v_sub_f32_e32 v246, v184, v84
	v_mov_b32_e32 v248, v84
	v_exp_f32_e32 v246, v246
	v_mov_b32_e32 v184, v84
	v_max3_f32 v85, v182, v85, v87
	v_sub_f32_e32 v247, v182, v85
	v_mov_b32_e32 v249, v85
	v_exp_f32_e32 v247, v247
	v_mov_b32_e32 v182, v85
	v_mfma_f32_16x16x32_bf16 v[238:241], v[52:55], v[112:115], 0
	v_sub_f32_e32 v120, v120, v248
	v_sub_f32_e32 v121, v121, v248
	v_sub_f32_e32 v122, v122, v248
	v_sub_f32_e32 v123, v123, v248
	v_sub_f32_e32 v124, v124, v248
	v_sub_f32_e32 v125, v125, v248
	v_sub_f32_e32 v126, v126, v248
	v_sub_f32_e32 v127, v127, v248
	v_sub_f32_e32 v128, v128, v249
	v_sub_f32_e32 v129, v129, v249
	v_mfma_f32_16x16x32_bf16 v[242:245], v[56:59], v[112:115], 0
	v_sub_f32_e32 v130, v130, v249
	v_sub_f32_e32 v131, v131, v249
	v_sub_f32_e32 v172, v172, v249
	v_sub_f32_e32 v173, v173, v249
	v_sub_f32_e32 v174, v174, v249
	v_sub_f32_e32 v175, v175, v249
	v_exp_f32_e32 v120, v120
	v_exp_f32_e32 v121, v121
	v_exp_f32_e32 v122, v122
	v_mfma_f32_16x16x32_bf16 v[176:179], v[60:63], v[108:111], v[176:179]
	v_exp_f32_e32 v123, v123
	v_exp_f32_e32 v124, v124
	v_exp_f32_e32 v125, v125
	v_exp_f32_e32 v126, v126
	v_exp_f32_e32 v127, v127
	v_exp_f32_e32 v128, v128
	v_exp_f32_e32 v129, v129
	v_exp_f32_e32 v130, v130
	v_exp_f32_e32 v131, v131
	v_exp_f32_e32 v172, v172
	v_mfma_f32_16x16x32_bf16 v[190:193], v[64:67], v[108:111], v[190:193]
	v_exp_f32_e32 v173, v173
	v_exp_f32_e32 v174, v174
	v_exp_f32_e32 v175, v175
	v_add_f32_e32 v84, v120, v121
	v_add_f32_e32 v86, v122, v123
	v_add_f32_e32 v84, v84, v86
	v_add_f32_e32 v86, v124, v125
	v_add_f32_e32 v84, v84, v86
	v_add_f32_e32 v86, v126, v127
	v_add_f32_e32 v84, v84, v86
	v_mfma_f32_16x16x32_bf16 v[238:241], v[60:63], v[116:119], v[238:241]
	v_fma_f32 v133, v133, v246, v84
	v_add_f32_e32 v85, v128, v129
	v_add_f32_e32 v87, v130, v131
	v_add_f32_e32 v85, v85, v87
	v_add_f32_e32 v87, v172, v173
	v_add_f32_e32 v85, v85, v87
	v_add_f32_e32 v87, v174, v175
	v_add_f32_e32 v85, v85, v87
	v_fma_f32 v132, v132, v247, v85
	v_cvt_pk_bf16_f32 v120, v120, v121
	v_mfma_f32_16x16x32_bf16 v[242:245], v[64:67], v[116:119], v[242:245]
	ds_read_b128 v[52:55], v250 offset:4096
	ds_read_b128 v[56:59], v250 offset:6144
	ds_read_b128 v[60:63], v251 offset:4096
	ds_read_b128 v[64:67], v251 offset:6144
	ds_read_b128 v[104:107], v254 offset:32768
	ds_read_b128 v[108:111], v255 offset:32768
	ds_read_b128 v[112:115], v254 offset:40960
	ds_read_b128 v[116:119], v255 offset:40960
	v_cvt_pk_bf16_f32 v121, v122, v123
	v_cvt_pk_bf16_f32 v122, v124, v125
	v_cvt_pk_bf16_f32 v123, v126, v127
	v_cvt_pk_bf16_f32 v128, v128, v129
	v_cvt_pk_bf16_f32 v129, v130, v131
	v_cvt_pk_bf16_f32 v130, v172, v173
	v_cvt_pk_bf16_f32 v131, v174, v175
	v_cmp_neq_f32_e32 vcc, 1.0, v246
	s_nop 1
	s_cbranch_vccz .Lwinf_r0
	v_mul_f32_e32 v100, v100, v246
	v_mul_f32_e32 v101, v101, v246
	v_mul_f32_e32 v102, v102, v246
	v_mul_f32_e32 v103, v103, v246
	v_mul_f32_e32 v96, v96, v246
	v_mul_f32_e32 v97, v97, v246
	v_mul_f32_e32 v98, v98, v246
	v_mul_f32_e32 v99, v99, v246
	v_mul_f32_e32 v92, v92, v246
	v_mul_f32_e32 v93, v93, v246
	v_mul_f32_e32 v94, v94, v246
	v_mul_f32_e32 v95, v95, v246
	v_mul_f32_e32 v88, v88, v246
	v_mul_f32_e32 v89, v89, v246
	v_mul_f32_e32 v90, v90, v246
	v_mul_f32_e32 v91, v91, v246

.Lwinf_x1:
	v_max3_f32 v84, v176, s75, v177
	v_max3_f32 v84, v84, v178, v179
	v_max3_f32 v84, v84, v190, v191
	v_max3_f32 v84, v84, v192, v193
	v_max3_f32 v85, v238, s75, v239
	v_mfma_f32_16x16x32_bf16 v[36:39], v[68:71], v[128:131], v[36:39]
	v_max3_f32 v85, v85, v240, v241
	v_max3_f32 v85, v85, v242, v243
	v_max3_f32 v85, v85, v244, v245
	v_mov_b32_e32 v86, v84
	v_mov_b32_e32 v87, v85
	s_nop 1
	v_permlane16_swap_b32_e32 v84, v86
	v_permlane16_swap_b32_e32 v85, v87
	v_max_f32_e32 v84, v84, v86
	v_max_f32_e32 v85, v85, v87
	v_mov_b32_e32 v86, v84
	v_mov_b32_e32 v87, v85
	s_nop 1
	v_permlane32_swap_b32_e32 v84, v86
	v_permlane32_swap_b32_e32 v85, v87
	v_mfma_f32_16x16x32_bf16 v[96:99], v[72:75], v[120:123], v[96:99]
	v_max3_f32 v84, v170, v84, v86
	v_sub_f32_e32 v246, v170, v84
	v_mov_b32_e32 v248, v84
	v_exp_f32_e32 v246, v246
	v_mov_b32_e32 v170, v84
	v_mfma_f32_16x16x32_bf16 v[32:35], v[72:75], v[128:131], v[32:35]
	v_max3_f32 v85, v188, v85, v87
	v_sub_f32_e32 v247, v188, v85
	v_mov_b32_e32 v249, v85
	v_exp_f32_e32 v247, v247
	v_mov_b32_e32 v188, v85
	v_mfma_f32_16x16x32_bf16 v[92:95], v[76:79], v[120:123], v[92:95]
	v_sub_f32_e32 v176, v176, v248
	v_sub_f32_e32 v177, v177, v248
	v_sub_f32_e32 v178, v178, v248
	v_sub_f32_e32 v179, v179, v248
	v_sub_f32_e32 v190, v190, v248
	v_mfma_f32_16x16x32_bf16 v[28:31], v[76:79], v[128:131], v[28:31]
	v_sub_f32_e32 v191, v191, v248
	v_sub_f32_e32 v192, v192, v248
	v_sub_f32_e32 v193, v193, v248
	v_sub_f32_e32 v238, v238, v249
	v_sub_f32_e32 v239, v239, v249
	v_mfma_f32_16x16x32_bf16 v[88:91], v[80:83], v[120:123], v[88:91]
	v_sub_f32_e32 v240, v240, v249
	v_sub_f32_e32 v241, v241, v249
	v_sub_f32_e32 v242, v242, v249
	v_sub_f32_e32 v243, v243, v249
	v_sub_f32_e32 v244, v244, v249
	v_mfma_f32_16x16x32_bf16 v[24:27], v[80:83], v[128:131], v[24:27]
	v_sub_f32_e32 v245, v245, v249
	v_exp_f32_e32 v176, v176
	v_exp_f32_e32 v177, v177
	v_exp_f32_e32 v178, v178
	s_waitcnt lgkmcnt(0)
	v_mfma_f32_16x16x32_bf16 v[120:123], v[52:55], v[104:107], 0
	v_exp_f32_e32 v179, v179
	v_exp_f32_e32 v190, v190
	v_exp_f32_e32 v191, v191
	v_exp_f32_e32 v192, v192
	v_exp_f32_e32 v193, v193
	v_mfma_f32_16x16x32_bf16 v[124:127], v[56:59], v[104:107], 0
	v_exp_f32_e32 v238, v238
	v_exp_f32_e32 v239, v239
	v_exp_f32_e32 v240, v240
	v_exp_f32_e32 v241, v241
	v_exp_f32_e32 v242, v242
	v_mfma_f32_16x16x32_bf16 v[128:131], v[52:55], v[112:115], 0
	v_exp_f32_e32 v243, v243
	v_exp_f32_e32 v244, v244
	v_exp_f32_e32 v245, v245
	v_add_f32_e32 v84, v176, v177
	v_add_f32_e32 v86, v178, v179
	v_mfma_f32_16x16x32_bf16 v[172:175], v[56:59], v[112:115], 0
	v_add_f32_e32 v84, v84, v86
	v_add_f32_e32 v86, v190, v191
	v_add_f32_e32 v84, v84, v86
	v_add_f32_e32 v86, v192, v193
	v_add_f32_e32 v84, v84, v86
	v_mfma_f32_16x16x32_bf16 v[120:123], v[60:63], v[108:111], v[120:123]
	v_fma_f32 v165, v165, v246, v84
	v_add_f32_e32 v85, v238, v239
	v_add_f32_e32 v87, v240, v241
	v_add_f32_e32 v85, v85, v87
	v_add_f32_e32 v87, v242, v243
	v_mfma_f32_16x16x32_bf16 v[124:127], v[64:67], v[108:111], v[124:127]
	v_add_f32_e32 v85, v85, v87
	v_add_f32_e32 v87, v244, v245
	v_add_f32_e32 v85, v85, v87
	v_fma_f32 v164, v164, v247, v85
	v_cvt_pk_bf16_f32 v176, v176, v177
	v_mfma_f32_16x16x32_bf16 v[128:131], v[60:63], v[116:119], v[128:131]
	v_cvt_pk_bf16_f32 v177, v178, v179
	v_cvt_pk_bf16_f32 v178, v190, v191
	v_cvt_pk_bf16_f32 v179, v192, v193
	v_cvt_pk_bf16_f32 v238, v238, v239
	v_cvt_pk_bf16_f32 v239, v240, v241
	v_mfma_f32_16x16x32_bf16 v[172:175], v[64:67], v[116:119], v[172:175]
	ds_read_b128 v[104:107], v254 offset:49152
	ds_read_b128 v[108:111], v255 offset:49152
	ds_read_b128 v[112:115], v254 offset:57344
	ds_read_b128 v[116:119], v255 offset:57344
	v_cvt_pk_bf16_f32 v240, v242, v243
	v_cvt_pk_bf16_f32 v241, v244, v245
	v_cmp_neq_f32_e32 vcc, 1.0, v246
	s_nop 1
	s_cbranch_vccz .Lwinf_r2
	v_mul_f32_e32 v44, v44, v246
	v_mul_f32_e32 v45, v45, v246
	v_mul_f32_e32 v46, v46, v246
	v_mul_f32_e32 v47, v47, v246
	v_mul_f32_e32 v40, v40, v246
	v_mul_f32_e32 v41, v41, v246
	v_mul_f32_e32 v42, v42, v246
	v_mul_f32_e32 v43, v43, v246
	v_mul_f32_e32 v20, v20, v246
	v_mul_f32_e32 v21, v21, v246
	v_mul_f32_e32 v22, v22, v246
	v_mul_f32_e32 v23, v23, v246
	v_mul_f32_e32 v16, v16, v246
	v_mul_f32_e32 v17, v17, v246
	v_mul_f32_e32 v18, v18, v246
	v_mul_f32_e32 v19, v19, v246

.Lwinf_x2:
	v_max3_f32 v84, v120, s75, v121
	v_max3_f32 v84, v84, v122, v123
	v_max3_f32 v84, v84, v124, v125
	v_max3_f32 v84, v84, v126, v127
	v_max3_f32 v85, v128, s75, v129
	v_mfma_f32_16x16x32_bf16 v[12:15], v[68:71], v[238:241], v[12:15]
	v_max3_f32 v85, v85, v130, v131
	v_max3_f32 v85, v85, v172, v173
	v_max3_f32 v85, v85, v174, v175
	v_mov_b32_e32 v86, v84
	v_mov_b32_e32 v87, v85
	s_nop 1
	v_permlane16_swap_b32_e32 v84, v86
	v_permlane16_swap_b32_e32 v85, v87
	v_max_f32_e32 v84, v84, v86
	v_max_f32_e32 v85, v85, v87
	v_mov_b32_e32 v86, v84
	v_mov_b32_e32 v87, v85
	s_nop 1
	v_permlane32_swap_b32_e32 v84, v86
	v_permlane32_swap_b32_e32 v85, v87
	v_mfma_f32_16x16x32_bf16 v[40:43], v[72:75], v[176:179], v[40:43]
	v_max3_f32 v84, v184, v84, v86
	v_sub_f32_e32 v246, v184, v84
	v_mov_b32_e32 v248, v84
	v_exp_f32_e32 v246, v246
	v_mov_b32_e32 v184, v84
	v_mfma_f32_16x16x32_bf16 v[8:11], v[72:75], v[238:241], v[8:11]
	v_max3_f32 v85, v182, v85, v87
	v_sub_f32_e32 v247, v182, v85
	v_mov_b32_e32 v249, v85
	v_exp_f32_e32 v247, v247
	v_mov_b32_e32 v182, v85
	v_mfma_f32_16x16x32_bf16 v[20:23], v[76:79], v[176:179], v[20:23]
	v_sub_f32_e32 v120, v120, v248
	v_sub_f32_e32 v121, v121, v248
	v_sub_f32_e32 v122, v122, v248
	v_sub_f32_e32 v123, v123, v248
	v_sub_f32_e32 v124, v124, v248
	v_mfma_f32_16x16x32_bf16 v[4:7], v[76:79], v[238:241], v[4:7]
	v_sub_f32_e32 v125, v125, v248
	v_sub_f32_e32 v126, v126, v248
	v_sub_f32_e32 v127, v127, v248
	v_sub_f32_e32 v128, v128, v249
	v_sub_f32_e32 v129, v129, v249
	v_mfma_f32_16x16x32_bf16 v[16:19], v[80:83], v[176:179], v[16:19]
	v_sub_f32_e32 v130, v130, v249
	v_sub_f32_e32 v131, v131, v249
	v_sub_f32_e32 v172, v172, v249
	v_sub_f32_e32 v173, v173, v249
	v_sub_f32_e32 v174, v174, v249
	v_mfma_f32_16x16x32_bf16 v[0:3], v[80:83], v[238:241], v[0:3]
	v_sub_f32_e32 v175, v175, v249
	v_exp_f32_e32 v120, v120
	v_exp_f32_e32 v121, v121
	v_exp_f32_e32 v122, v122
	ds_read_b64 v[68:69], v196 offset:8192
	ds_read_b64 v[70:71], v197 offset:8192
	ds_read_b64 v[72:73], v196 offset:10240
	ds_read_b64 v[74:75], v197 offset:10240
	ds_read_b64 v[76:77], v196 offset:12288
	ds_read_b64 v[78:79], v197 offset:12288
	ds_read_b64 v[80:81], v196 offset:14336
	ds_read_b64 v[82:83], v197 offset:14336
	s_waitcnt lgkmcnt(8)
	v_mfma_f32_16x16x32_bf16 v[176:179], v[52:55], v[104:107], 0
	v_exp_f32_e32 v123, v123
	v_exp_f32_e32 v124, v124
	v_exp_f32_e32 v125, v125
	v_exp_f32_e32 v126, v126
	v_exp_f32_e32 v127, v127
	v_mfma_f32_16x16x32_bf16 v[190:193], v[56:59], v[104:107], 0
	v_exp_f32_e32 v128, v128
	v_exp_f32_e32 v129, v129
	v_exp_f32_e32 v130, v130
	v_exp_f32_e32 v131, v131
	v_exp_f32_e32 v172, v172
	v_mfma_f32_16x16x32_bf16 v[238:241], v[52:55], v[112:115], 0
	v_exp_f32_e32 v173, v173
	v_exp_f32_e32 v174, v174
	v_exp_f32_e32 v175, v175
	v_add_f32_e32 v84, v120, v121
	v_add_f32_e32 v86, v122, v123
	v_mfma_f32_16x16x32_bf16 v[242:245], v[56:59], v[112:115], 0
	v_add_f32_e32 v84, v84, v86
	v_add_f32_e32 v86, v124, v125
	v_add_f32_e32 v84, v84, v86
	v_add_f32_e32 v86, v126, v127
	v_add_f32_e32 v84, v84, v86
	v_mfma_f32_16x16x32_bf16 v[176:179], v[60:63], v[108:111], v[176:179]
	v_fma_f32 v133, v133, v246, v84
	v_add_f32_e32 v85, v128, v129
	v_add_f32_e32 v87, v130, v131
	v_add_f32_e32 v85, v85, v87
	v_add_f32_e32 v87, v172, v173
	v_mfma_f32_16x16x32_bf16 v[190:193], v[64:67], v[108:111], v[190:193]
	v_add_f32_e32 v85, v85, v87
	v_add_f32_e32 v87, v174, v175
	v_add_f32_e32 v85, v85, v87
	v_fma_f32 v132, v132, v247, v85
	v_cvt_pk_bf16_f32 v120, v120, v121
	v_mfma_f32_16x16x32_bf16 v[238:241], v[60:63], v[116:119], v[238:241]
	v_cvt_pk_bf16_f32 v121, v122, v123
	v_cvt_pk_bf16_f32 v122, v124, v125
	v_cvt_pk_bf16_f32 v123, v126, v127
	v_cvt_pk_bf16_f32 v128, v128, v129
	v_cvt_pk_bf16_f32 v129, v130, v131
	v_mfma_f32_16x16x32_bf16 v[242:245], v[64:67], v[116:119], v[242:245]
	v_cvt_pk_bf16_f32 v130, v172, v173
	v_cvt_pk_bf16_f32 v131, v174, v175
	v_cmp_neq_f32_e32 vcc, 1.0, v246
	s_nop 1
	s_cbranch_vccz .Lwinf_r4
	v_mul_f32_e32 v100, v100, v246
	v_mul_f32_e32 v101, v101, v246
	v_mul_f32_e32 v102, v102, v246
	v_mul_f32_e32 v103, v103, v246
	v_mul_f32_e32 v96, v96, v246
	v_mul_f32_e32 v97, v97, v246
	v_mul_f32_e32 v98, v98, v246
	v_mul_f32_e32 v99, v99, v246
	v_mul_f32_e32 v92, v92, v246
	v_mul_f32_e32 v93, v93, v246
	v_mul_f32_e32 v94, v94, v246
	v_mul_f32_e32 v95, v95, v246
	v_mul_f32_e32 v88, v88, v246
	v_mul_f32_e32 v89, v89, v246
	v_mul_f32_e32 v90, v90, v246
	v_mul_f32_e32 v91, v91, v246

.Lwinf_x3:
	v_max3_f32 v84, v176, s75, v177
	v_max3_f32 v84, v84, v178, v179
	v_max3_f32 v84, v84, v190, v191
	v_max3_f32 v84, v84, v192, v193
	v_max3_f32 v85, v238, s75, v239
	v_max3_f32 v85, v85, v240, v241
	v_max3_f32 v85, v85, v242, v243
	v_max3_f32 v85, v85, v244, v245
	v_mov_b32_e32 v86, v84
	v_mov_b32_e32 v87, v85
	s_nop 1
	v_permlane16_swap_b32_e32 v84, v86
	v_permlane16_swap_b32_e32 v85, v87
	v_max_f32_e32 v84, v84, v86
	v_max_f32_e32 v85, v85, v87
	v_mov_b32_e32 v86, v84
	v_mov_b32_e32 v87, v85
	s_nop 1
	v_permlane32_swap_b32_e32 v84, v86
	v_permlane32_swap_b32_e32 v85, v87
	v_mfma_f32_16x16x32_bf16 v[36:39], v[68:71], v[128:131], v[36:39]
	v_max3_f32 v84, v170, v84, v86
	v_sub_f32_e32 v246, v170, v84
	v_mov_b32_e32 v248, v84
	v_exp_f32_e32 v246, v246
	v_mov_b32_e32 v170, v84
	v_max3_f32 v85, v188, v85, v87
	v_sub_f32_e32 v247, v188, v85
	v_mov_b32_e32 v249, v85
	v_exp_f32_e32 v247, v247
	v_mov_b32_e32 v188, v85
	v_mfma_f32_16x16x32_bf16 v[96:99], v[72:75], v[120:123], v[96:99]
	v_sub_f32_e32 v176, v176, v248
	v_sub_f32_e32 v177, v177, v248
	v_sub_f32_e32 v178, v178, v248
	v_sub_f32_e32 v179, v179, v248
	v_sub_f32_e32 v190, v190, v248
	v_sub_f32_e32 v191, v191, v248
	v_sub_f32_e32 v192, v192, v248
	v_sub_f32_e32 v193, v193, v248
	v_sub_f32_e32 v238, v238, v249
	v_sub_f32_e32 v239, v239, v249
	v_mfma_f32_16x16x32_bf16 v[32:35], v[72:75], v[128:131], v[32:35]
	v_sub_f32_e32 v240, v240, v249
	v_sub_f32_e32 v241, v241, v249
	v_sub_f32_e32 v242, v242, v249
	v_sub_f32_e32 v243, v243, v249
	v_sub_f32_e32 v244, v244, v249
	v_sub_f32_e32 v245, v245, v249
	v_exp_f32_e32 v176, v176
	v_exp_f32_e32 v177, v177
	v_exp_f32_e32 v178, v178
	v_mfma_f32_16x16x32_bf16 v[92:95], v[76:79], v[120:123], v[92:95]
	v_exp_f32_e32 v179, v179
	v_exp_f32_e32 v190, v190
	v_exp_f32_e32 v191, v191
	v_exp_f32_e32 v192, v192
	v_exp_f32_e32 v193, v193
	v_exp_f32_e32 v238, v238
	v_exp_f32_e32 v239, v239
	v_exp_f32_e32 v240, v240
	v_exp_f32_e32 v241, v241
	v_exp_f32_e32 v242, v242
	v_mfma_f32_16x16x32_bf16 v[28:31], v[76:79], v[128:131], v[28:31]
	v_exp_f32_e32 v243, v243
	v_exp_f32_e32 v244, v244
	v_exp_f32_e32 v245, v245
	v_add_f32_e32 v84, v176, v177
	v_add_f32_e32 v86, v178, v179
	v_add_f32_e32 v84, v84, v86
	v_add_f32_e32 v86, v190, v191
	v_add_f32_e32 v84, v84, v86
	v_add_f32_e32 v86, v192, v193
	v_add_f32_e32 v84, v84, v86
	v_mfma_f32_16x16x32_bf16 v[88:91], v[80:83], v[120:123], v[88:91]
	v_fma_f32 v165, v165, v246, v84
	v_add_f32_e32 v85, v238, v239
	v_add_f32_e32 v87, v240, v241
	v_add_f32_e32 v85, v85, v87
	v_add_f32_e32 v87, v242, v243
	v_add_f32_e32 v85, v85, v87
	v_add_f32_e32 v87, v244, v245
	v_add_f32_e32 v85, v85, v87
	v_fma_f32 v164, v164, v247, v85
	v_cvt_pk_bf16_f32 v176, v176, v177
	v_mfma_f32_16x16x32_bf16 v[24:27], v[80:83], v[128:131], v[24:27]
	v_cvt_pk_bf16_f32 v177, v178, v179
	v_cvt_pk_bf16_f32 v178, v190, v191
	v_cvt_pk_bf16_f32 v179, v192, v193
	v_cvt_pk_bf16_f32 v238, v238, v239
	v_cvt_pk_bf16_f32 v239, v240, v241
	v_cvt_pk_bf16_f32 v240, v242, v243
	v_cvt_pk_bf16_f32 v241, v244, v245
	v_cmp_neq_f32_e32 vcc, 1.0, v246
	s_nop 1
	s_cbranch_vccz .Lwinf_r6
	v_mul_f32_e32 v44, v44, v246
	v_mul_f32_e32 v45, v45, v246
	v_mul_f32_e32 v46, v46, v246
	v_mul_f32_e32 v47, v47, v246
	v_mul_f32_e32 v40, v40, v246
	v_mul_f32_e32 v41, v41, v246
	v_mul_f32_e32 v42, v42, v246
	v_mul_f32_e32 v43, v43, v246
	v_mul_f32_e32 v20, v20, v246
	v_mul_f32_e32 v21, v21, v246
	v_mul_f32_e32 v22, v22, v246
	v_mul_f32_e32 v23, v23, v246
	v_mul_f32_e32 v16, v16, v246
	v_mul_f32_e32 v17, v17, v246
	v_mul_f32_e32 v18, v18, v246
	v_mul_f32_e32 v19, v19, v246
